# speedup vs baseline: 1.0031x; 1.0031x over previous
; template <int EPI, int MB, int NB> ...
;     ...
;     u16* dst = (u16*)(e.wsb + doff);
;     const float qs = region == 0 ? QSCALE : 1.f;
; #pragma unroll
;     for (int m = 0; m < MB; ++m) {
;       const int lr = lrow0 + m * 16;
;       const float rs = s_rstd[lr] * qs;
;       u16* orow = dst + (size_t)(brow + lr) * ld + (col0 - cb);
;       u32x2 ob[2];
; #pragma unroll
;       for (int n = 0; n < NB; ++n) {
;         float v[4];
; #pragma unroll
;         for (int j = 0; j < 4; ++j) { v[j] = acc[m][n][j] * rs; if (sig) v[j] = __builtin_amdgcn_rcpf(1.f + __expf(-v[j])); }
;         ob[n][0] = pk_bf16(v[0], v[1]); ob[n][1] = pk_bf16(v[2], v[3]);
;       }
;       *(i32x4*)(orow + wofs) = widen16(ob[0], ob[1]);
;     }
.Lwin_fast_1:
	v_lshl_add_u32 v131, v130, 2, s19
	ds_read2_b32 v[132:133], v131 offset1:16
	s_add_u32 s6, s56, s6
	s_addc_u32 s7, s57, s7
	s_add_i32 s13, s23, s24
	v_add_u32_e32 v128, s13, v128
	s_waitcnt lgkmcnt(0)
	v_mul_f32_e32 v132, s29, v132
	v_mul_f32_e32 v124, v124, v132
	v_mul_f32_e32 v125, v125, v132
	v_mul_f32_e32 v126, v126, v132
	v_mul_f32_e32 v127, v127, v132
	v_mul_f32_e32 v120, v120, v132
	v_mul_f32_e32 v121, v121, v132
	v_mul_f32_e32 v122, v122, v132
	v_mul_f32_e32 v123, v123, v132
	v_ashrrev_i32_e32 v129, 31, v128
	v_lshl_add_u64 v[128:129], v[128:129], 1, s[6:7]
	v_add_u32_e32 v130, s28, v130
	v_lshl_add_u64 v[128:129], v[194:195], 1, v[128:129]
	v_cvt_pk_bf16_f32 v124, v124, v125
	v_cvt_pk_bf16_f32 v125, v126, v127
	v_cvt_pk_bf16_f32 v126, v120, v121
	v_cvt_pk_bf16_f32 v127, v122, v123
	v_mad_i64_i32 v[120:121], s[6:7], s12, v130, 0
	s_nop 1
	v_permlane16_swap_b32_e32 v124, v126
	v_permlane16_swap_b32_e32 v125, v127
	v_lshl_add_u64 v[120:121], v[120:121], 1, v[128:129]
	global_store_dwordx4 v[120:121], v[124:127], off
	v_mul_f32_e32 v120, s29, v133
	v_mul_f32_e32 v116, v116, v120
	v_mul_f32_e32 v117, v117, v120
	v_mul_f32_e32 v118, v118, v120
	v_mul_f32_e32 v119, v119, v120
	v_mul_f32_e32 v112, v112, v120
	v_mul_f32_e32 v113, v113, v120
	v_mul_f32_e32 v114, v114, v120
	v_mul_f32_e32 v115, v115, v120
	v_add_u32_e32 v121, 16, v130
	v_cvt_pk_bf16_f32 v116, v116, v117
	v_cvt_pk_bf16_f32 v117, v118, v119
	v_cvt_pk_bf16_f32 v118, v112, v113
	v_cvt_pk_bf16_f32 v119, v114, v115
	v_mad_i64_i32 v[112:113], s[6:7], s12, v121, 0
	s_nop 1
	v_permlane16_swap_b32_e32 v116, v118
	v_permlane16_swap_b32_e32 v117, v119
	v_lshl_add_u64 v[112:113], v[112:113], 1, v[128:129]
	global_store_dwordx4 v[112:113], v[116:119], off
	ds_read2_b32 v[112:113], v131 offset0:32 offset1:48
	v_add_u32_e32 v114, 32, v130
	s_waitcnt lgkmcnt(0)
	v_mul_f32_e32 v112, s29, v112
	v_mul_f32_e32 v108, v108, v112
	v_mul_f32_e32 v109, v109, v112
	v_mul_f32_e32 v110, v110, v112
	v_mul_f32_e32 v111, v111, v112
	v_mul_f32_e32 v104, v104, v112
	v_mul_f32_e32 v105, v105, v112
	v_mul_f32_e32 v106, v106, v112
	v_mul_f32_e32 v107, v107, v112
	v_cvt_pk_bf16_f32 v108, v108, v109
	v_cvt_pk_bf16_f32 v109, v110, v111
	v_cvt_pk_bf16_f32 v110, v104, v105
	v_cvt_pk_bf16_f32 v111, v106, v107
	v_mad_i64_i32 v[104:105], s[6:7], s12, v114, 0
	s_nop 1
	v_permlane16_swap_b32_e32 v108, v110
	v_permlane16_swap_b32_e32 v109, v111
	v_lshl_add_u64 v[104:105], v[104:105], 1, v[128:129]
	global_store_dwordx4 v[104:105], v[108:111], off
	v_mul_f32_e32 v104, s29, v113
	v_mul_f32_e32 v100, v100, v104
	v_mul_f32_e32 v101, v101, v104
	v_mul_f32_e32 v102, v102, v104
	v_mul_f32_e32 v103, v103, v104
	v_mul_f32_e32 v96, v96, v104
	v_mul_f32_e32 v97, v97, v104
	v_mul_f32_e32 v98, v98, v104
	v_mul_f32_e32 v99, v99, v104
	v_add_u32_e32 v105, 48, v130
	v_cvt_pk_bf16_f32 v100, v100, v101
	v_cvt_pk_bf16_f32 v101, v102, v103
	v_cvt_pk_bf16_f32 v102, v96, v97
	v_cvt_pk_bf16_f32 v103, v98, v99
	v_mad_i64_i32 v[96:97], s[6:7], s12, v105, 0
	s_nop 1
	v_permlane16_swap_b32_e32 v100, v102
	v_permlane16_swap_b32_e32 v101, v103
	v_lshl_add_u64 v[96:97], v[96:97], 1, v[128:129]
	global_store_dwordx4 v[96:97], v[100:103], off
	s_branch .Lwin_join_1
.Lwin_fast_2:
	v_lshl_add_u32 v99, v98, 2, s19
	ds_read2_b32 v[100:101], v99 offset1:16
	s_add_u32 s6, s56, s6
	s_addc_u32 s7, s57, s7
	s_add_i32 s23, s23, s24
	v_add_u32_e32 v96, s23, v96
	s_waitcnt lgkmcnt(0)
	v_mul_f32_e32 v100, s29, v100
	v_mul_f32_e32 v92, v92, v100
	v_mul_f32_e32 v93, v93, v100
	v_mul_f32_e32 v94, v94, v100
	v_mul_f32_e32 v95, v95, v100
	v_mul_f32_e32 v88, v88, v100
	v_mul_f32_e32 v89, v89, v100
	v_mul_f32_e32 v90, v90, v100
	v_mul_f32_e32 v91, v91, v100
	v_ashrrev_i32_e32 v97, 31, v96
	v_lshl_add_u64 v[96:97], v[96:97], 1, s[6:7]
	v_add_u32_e32 v98, s28, v98
	v_lshl_add_u64 v[96:97], v[194:195], 1, v[96:97]
	v_cvt_pk_bf16_f32 v92, v92, v93
	v_cvt_pk_bf16_f32 v93, v94, v95
	v_cvt_pk_bf16_f32 v94, v88, v89
	v_cvt_pk_bf16_f32 v95, v90, v91
	v_mad_i64_i32 v[88:89], s[6:7], vcc_lo, v98, 0
	s_nop 1
	v_permlane16_swap_b32_e32 v92, v94
	v_permlane16_swap_b32_e32 v93, v95
	v_lshl_add_u64 v[88:89], v[88:89], 1, v[96:97]
	global_store_dwordx4 v[88:89], v[92:95], off
	v_mul_f32_e32 v88, s29, v101
	v_mul_f32_e32 v84, v84, v88
	v_mul_f32_e32 v85, v85, v88
	v_mul_f32_e32 v86, v86, v88
	v_mul_f32_e32 v87, v87, v88
	v_mul_f32_e32 v80, v80, v88
	v_mul_f32_e32 v81, v81, v88
	v_mul_f32_e32 v82, v82, v88
	v_mul_f32_e32 v83, v83, v88
	v_add_u32_e32 v89, 16, v98
	v_cvt_pk_bf16_f32 v84, v84, v85
	v_cvt_pk_bf16_f32 v85, v86, v87
	v_cvt_pk_bf16_f32 v86, v80, v81
	v_cvt_pk_bf16_f32 v87, v82, v83
	v_mad_i64_i32 v[80:81], s[6:7], vcc_lo, v89, 0
	s_nop 1
	v_permlane16_swap_b32_e32 v84, v86
	v_permlane16_swap_b32_e32 v85, v87
	v_lshl_add_u64 v[80:81], v[80:81], 1, v[96:97]
	global_store_dwordx4 v[80:81], v[84:87], off
	ds_read2_b32 v[80:81], v99 offset0:32 offset1:48
	v_add_u32_e32 v82, 32, v98
	s_waitcnt lgkmcnt(0)
	v_mul_f32_e32 v80, s29, v80
	v_mul_f32_e32 v76, v76, v80
	v_mul_f32_e32 v77, v77, v80
	v_mul_f32_e32 v78, v78, v80
	v_mul_f32_e32 v79, v79, v80
	v_mul_f32_e32 v72, v72, v80
	v_mul_f32_e32 v73, v73, v80
	v_mul_f32_e32 v74, v74, v80
	v_mul_f32_e32 v75, v75, v80
	v_cvt_pk_bf16_f32 v76, v76, v77
	v_cvt_pk_bf16_f32 v77, v78, v79
	v_cvt_pk_bf16_f32 v78, v72, v73
	v_cvt_pk_bf16_f32 v79, v74, v75
	v_mad_i64_i32 v[72:73], s[6:7], vcc_lo, v82, 0
	s_nop 1
	v_permlane16_swap_b32_e32 v76, v78
	v_permlane16_swap_b32_e32 v77, v79
	v_lshl_add_u64 v[72:73], v[72:73], 1, v[96:97]
	global_store_dwordx4 v[72:73], v[76:79], off
	v_mul_f32_e32 v72, s29, v81
	v_mul_f32_e32 v68, v68, v72
	v_mul_f32_e32 v69, v69, v72
	v_mul_f32_e32 v70, v70, v72
	v_mul_f32_e32 v71, v71, v72
	v_mul_f32_e32 v64, v64, v72
	v_mul_f32_e32 v65, v65, v72
	v_mul_f32_e32 v66, v66, v72
	v_mul_f32_e32 v67, v67, v72
	v_add_u32_e32 v73, 48, v98
	v_cvt_pk_bf16_f32 v68, v68, v69
	v_cvt_pk_bf16_f32 v69, v70, v71
	v_cvt_pk_bf16_f32 v70, v64, v65
	v_cvt_pk_bf16_f32 v71, v66, v67
	v_mad_i64_i32 v[64:65], s[6:7], vcc_lo, v73, 0
	s_nop 1
	v_permlane16_swap_b32_e32 v68, v70
	v_permlane16_swap_b32_e32 v69, v71
	v_lshl_add_u64 v[64:65], v[64:65], 1, v[96:97]
	global_store_dwordx4 v[64:65], v[68:71], off
	s_branch .Lwin_join_2
; template <int EPI, int MB, int NB> ...
;     ...
;     u16* dst = (u16*)(e.wsb + doff);
;     const float qs = region == 0 ? QSCALE : 1.f;
; #pragma unroll
;     for (int m = 0; m < MB; ++m) {
;       const int lr = lrow0 + m * 16;
;       const float rs = s_rstd[lr] * qs;
;       u16* orow = dst + (size_t)(brow + lr) * ld + (col0 - cb);
;       u32x2 ob[2];
; #pragma unroll
;       for (int n = 0; n < NB; ++n) {
;         float v[4];
; #pragma unroll
;         for (int j = 0; j < 4; ++j) { v[j] = acc[m][n][j] * rs; if (sig) v[j] = __builtin_amdgcn_rcpf(1.f + __expf(-v[j])); }
;         ob[n][0] = pk_bf16(v[0], v[1]); ob[n][1] = pk_bf16(v[2], v[3]);
;       }
;       *(i32x4*)(orow + wofs) = widen16(ob[0], ob[1]);
;     }
.Lwin_fast_3:
	v_lshl_add_u32 v67, v66, 2, s19
	ds_read2_b32 v[68:69], v67 offset1:16
	s_add_u32 s6, s56, s6
	s_addc_u32 s7, s57, s7
	s_add_i32 s23, s23, s24
	v_add_u32_e32 v64, s23, v64
	s_waitcnt lgkmcnt(0)
	v_mul_f32_e32 v68, s29, v68
	v_mul_f32_e32 v60, v60, v68
	v_mul_f32_e32 v61, v61, v68
	v_mul_f32_e32 v62, v62, v68
	v_mul_f32_e32 v63, v63, v68
	v_mul_f32_e32 v56, v56, v68
	v_mul_f32_e32 v57, v57, v68
	v_mul_f32_e32 v58, v58, v68
	v_mul_f32_e32 v59, v59, v68
	v_ashrrev_i32_e32 v65, 31, v64
	v_lshl_add_u64 v[64:65], v[64:65], 1, s[6:7]
	v_add_u32_e32 v66, s28, v66
	v_lshl_add_u64 v[64:65], v[194:195], 1, v[64:65]
	v_cvt_pk_bf16_f32 v60, v60, v61
	v_cvt_pk_bf16_f32 v61, v62, v63
	v_cvt_pk_bf16_f32 v62, v56, v57
	v_cvt_pk_bf16_f32 v63, v58, v59
	v_mad_i64_i32 v[56:57], s[6:7], vcc_lo, v66, 0
	s_nop 1
	v_permlane16_swap_b32_e32 v60, v62
	v_permlane16_swap_b32_e32 v61, v63
	v_lshl_add_u64 v[56:57], v[56:57], 1, v[64:65]
	global_store_dwordx4 v[56:57], v[60:63], off
	v_mul_f32_e32 v56, s29, v69
	v_mul_f32_e32 v52, v52, v56
	v_mul_f32_e32 v53, v53, v56
	v_mul_f32_e32 v54, v54, v56
	v_mul_f32_e32 v55, v55, v56
	v_mul_f32_e32 v48, v48, v56
	v_mul_f32_e32 v49, v49, v56
	v_mul_f32_e32 v50, v50, v56
	v_mul_f32_e32 v51, v51, v56
	v_add_u32_e32 v57, 16, v66
	v_cvt_pk_bf16_f32 v52, v52, v53
	v_cvt_pk_bf16_f32 v53, v54, v55
	v_cvt_pk_bf16_f32 v54, v48, v49
	v_cvt_pk_bf16_f32 v55, v50, v51
	v_mad_i64_i32 v[48:49], s[6:7], vcc_lo, v57, 0
	s_nop 1
	v_permlane16_swap_b32_e32 v52, v54
	v_permlane16_swap_b32_e32 v53, v55
	v_lshl_add_u64 v[48:49], v[48:49], 1, v[64:65]
	global_store_dwordx4 v[48:49], v[52:55], off
	ds_read2_b32 v[48:49], v67 offset0:32 offset1:48
	v_add_u32_e32 v50, 32, v66
	s_waitcnt lgkmcnt(0)
	v_mul_f32_e32 v48, s29, v48
	v_mul_f32_e32 v44, v44, v48
	v_mul_f32_e32 v45, v45, v48
	v_mul_f32_e32 v46, v46, v48
	v_mul_f32_e32 v47, v47, v48
	v_mul_f32_e32 v40, v40, v48
	v_mul_f32_e32 v41, v41, v48
	v_mul_f32_e32 v42, v42, v48
	v_mul_f32_e32 v43, v43, v48
	v_cvt_pk_bf16_f32 v44, v44, v45
	v_cvt_pk_bf16_f32 v45, v46, v47
	v_cvt_pk_bf16_f32 v46, v40, v41
	v_cvt_pk_bf16_f32 v47, v42, v43
	v_mad_i64_i32 v[40:41], s[6:7], vcc_lo, v50, 0
	s_nop 1
	v_permlane16_swap_b32_e32 v44, v46
	v_permlane16_swap_b32_e32 v45, v47
	v_lshl_add_u64 v[40:41], v[40:41], 1, v[64:65]
	global_store_dwordx4 v[40:41], v[44:47], off
	v_mul_f32_e32 v40, s29, v49
	v_mul_f32_e32 v36, v36, v40
	v_mul_f32_e32 v37, v37, v40
	v_mul_f32_e32 v38, v38, v40
	v_mul_f32_e32 v39, v39, v40
	v_mul_f32_e32 v32, v32, v40
	v_mul_f32_e32 v33, v33, v40
	v_mul_f32_e32 v34, v34, v40
	v_mul_f32_e32 v35, v35, v40
	v_add_u32_e32 v41, 48, v66
	v_cvt_pk_bf16_f32 v36, v36, v37
	v_cvt_pk_bf16_f32 v37, v38, v39
	v_cvt_pk_bf16_f32 v38, v32, v33
	v_cvt_pk_bf16_f32 v39, v34, v35
	v_mad_i64_i32 v[32:33], s[6:7], vcc_lo, v41, 0
	s_nop 1
	v_permlane16_swap_b32_e32 v36, v38
	v_permlane16_swap_b32_e32 v37, v39
	v_lshl_add_u64 v[32:33], v[32:33], 1, v[64:65]
	global_store_dwordx4 v[32:33], v[36:39], off
	s_branch .Lwin_join_3
.Lwin_fast_4:
	v_lshl_add_u32 v35, v34, 2, s19
	ds_read2_b32 v[36:37], v35 offset1:16
	s_add_u32 s6, s56, s6
	s_addc_u32 s7, s57, s7
	s_add_i32 s13, s29, s24
	v_add_u32_e32 v32, s13, v32
	s_waitcnt lgkmcnt(0)
	v_mul_f32_e32 v36, s23, v36
	v_mul_f32_e32 v28, v28, v36
	v_mul_f32_e32 v29, v29, v36
	v_mul_f32_e32 v30, v30, v36
	v_mul_f32_e32 v31, v31, v36
	v_mul_f32_e32 v24, v24, v36
	v_mul_f32_e32 v25, v25, v36
	v_mul_f32_e32 v26, v26, v36
	v_mul_f32_e32 v27, v27, v36
	v_ashrrev_i32_e32 v33, 31, v32
	v_lshl_add_u64 v[32:33], v[32:33], 1, s[6:7]
	v_add_u32_e32 v34, s28, v34
	v_lshl_add_u64 v[32:33], v[194:195], 1, v[32:33]
	v_cvt_pk_bf16_f32 v28, v28, v29
	v_cvt_pk_bf16_f32 v29, v30, v31
	v_cvt_pk_bf16_f32 v30, v24, v25
	v_cvt_pk_bf16_f32 v31, v26, v27
	v_mad_i64_i32 v[24:25], s[6:7], s12, v34, 0
	s_nop 1
	v_permlane16_swap_b32_e32 v28, v30
	v_permlane16_swap_b32_e32 v29, v31
	v_lshl_add_u64 v[24:25], v[24:25], 1, v[32:33]
	global_store_dwordx4 v[24:25], v[28:31], off
	v_mul_f32_e32 v24, s23, v37
	v_mul_f32_e32 v20, v20, v24
	v_mul_f32_e32 v21, v21, v24
	v_mul_f32_e32 v22, v22, v24
	v_mul_f32_e32 v23, v23, v24
	v_mul_f32_e32 v16, v16, v24
	v_mul_f32_e32 v17, v17, v24
	v_mul_f32_e32 v18, v18, v24
	v_mul_f32_e32 v19, v19, v24
	v_add_u32_e32 v25, 16, v34
	v_cvt_pk_bf16_f32 v20, v20, v21
	v_cvt_pk_bf16_f32 v21, v22, v23
	v_cvt_pk_bf16_f32 v22, v16, v17
	v_cvt_pk_bf16_f32 v23, v18, v19
	v_mad_i64_i32 v[16:17], s[6:7], s12, v25, 0
	s_nop 1
	v_permlane16_swap_b32_e32 v20, v22
	v_permlane16_swap_b32_e32 v21, v23
	v_lshl_add_u64 v[16:17], v[16:17], 1, v[32:33]
	global_store_dwordx4 v[16:17], v[20:23], off
	ds_read2_b32 v[16:17], v35 offset0:32 offset1:48
	v_add_u32_e32 v18, 32, v34
	s_waitcnt lgkmcnt(0)
	v_mul_f32_e32 v16, s23, v16
	v_mul_f32_e32 v12, v12, v16
	v_mul_f32_e32 v13, v13, v16
	v_mul_f32_e32 v14, v14, v16
	v_mul_f32_e32 v15, v15, v16
	v_mul_f32_e32 v8, v8, v16
	v_mul_f32_e32 v9, v9, v16
	v_mul_f32_e32 v10, v10, v16
	v_mul_f32_e32 v11, v11, v16
	v_cvt_pk_bf16_f32 v12, v12, v13
	v_cvt_pk_bf16_f32 v13, v14, v15
	v_cvt_pk_bf16_f32 v14, v8, v9
	v_cvt_pk_bf16_f32 v15, v10, v11
	v_mad_i64_i32 v[8:9], s[6:7], s12, v18, 0
	s_nop 1
	v_permlane16_swap_b32_e32 v12, v14
	v_permlane16_swap_b32_e32 v13, v15
	v_lshl_add_u64 v[8:9], v[8:9], 1, v[32:33]
	global_store_dwordx4 v[8:9], v[12:15], off
	v_mul_f32_e32 v8, s23, v17
	v_mul_f32_e32 v4, v4, v8
	v_mul_f32_e32 v5, v5, v8
	v_mul_f32_e32 v6, v6, v8
	v_mul_f32_e32 v7, v7, v8
	v_mul_f32_e32 v0, v0, v8
	v_mul_f32_e32 v1, v1, v8
	v_mul_f32_e32 v2, v2, v8
	v_mul_f32_e32 v3, v3, v8
	v_add_u32_e32 v9, 48, v34
	v_cvt_pk_bf16_f32 v4, v4, v5
	v_cvt_pk_bf16_f32 v5, v6, v7
	v_cvt_pk_bf16_f32 v6, v0, v1
	v_cvt_pk_bf16_f32 v7, v2, v3
	v_mad_i64_i32 v[0:1], s[6:7], s12, v9, 0
	s_nop 1
	v_permlane16_swap_b32_e32 v4, v6
	v_permlane16_swap_b32_e32 v5, v7
	v_lshl_add_u64 v[0:1], v[0:1], 1, v[32:33]
	s_mov_b64 s[6:7], 0
	global_store_dwordx4 v[0:1], v[4:7], off
	s_branch .Lwin_join_4

; template <int EPI, int MB, int NB> ...
;     ...
;     u16* dst = (u16*)(e.wsb + doff);
;     const float qs = region == 0 ? QSCALE : 1.f;
; #pragma unroll
;     for (int m = 0; m < MB; ++m) {
;       const int lr = lrow0 + m * 16;
;       const float rs = s_rstd[lr] * qs;
;       u16* orow = dst + (size_t)(brow + lr) * ld + (col0 - cb);
;       u32x2 ob[2];
; #pragma unroll
;       for (int n = 0; n < NB; ++n) {
;         float v[4];
; #pragma unroll
;         for (int j = 0; j < 4; ++j) { v[j] = acc[m][n][j] * rs; if (sig) v[j] = __builtin_amdgcn_rcpf(1.f + __expf(-v[j])); }
;         ob[n][0] = pk_bf16(v[0], v[1]); ob[n][1] = pk_bf16(v[2], v[3]);
;       }
;       *(i32x4*)(orow + wofs) = widen16(ob[0], ob[1]);
;     }
.LBB0_218:
	s_cbranch_vccz .Lwin_fast_1
	v_lshl_add_u32 v131, v130, 2, s19
	ds_read2_b32 v[132:133], v131 offset1:16
	s_add_u32 s6, s56, s6
	s_addc_u32 s7, s57, s7
	s_add_i32 s13, s23, s24
	v_add_u32_e32 v128, s13, v128
	s_waitcnt lgkmcnt(0)
	v_mul_f32_e32 v132, s29, v132
	v_mul_f32_e32 v124, v124, v132
	v_mul_f32_e32 v134, 0xbfb8aa3b, v124
	v_exp_f32_e32 v134, v134
	v_mul_f32_e32 v125, v125, v132
	v_mul_f32_e32 v126, v126, v132
	v_mul_f32_e32 v127, v127, v132
	v_add_f32_e32 v134, 1.0, v134
	v_rcp_f32_e32 v134, v134
	v_mul_f32_e32 v120, v120, v132
	v_mul_f32_e32 v121, v121, v132
	v_mul_f32_e32 v122, v122, v132
	v_cndmask_b32_e32 v124, v124, v134, vcc
	v_mul_f32_e32 v134, 0xbfb8aa3b, v125
	v_exp_f32_e32 v134, v134
	v_mul_f32_e32 v123, v123, v132
	v_ashrrev_i32_e32 v129, 31, v128
	v_lshl_add_u64 v[128:129], v[128:129], 1, s[6:7]
	v_add_f32_e32 v134, 1.0, v134
	v_rcp_f32_e32 v134, v134
	v_add_u32_e32 v130, s28, v130
	v_lshl_add_u64 v[128:129], v[194:195], 1, v[128:129]
	v_cndmask_b32_e32 v125, v125, v134, vcc
	v_mul_f32_e32 v134, 0xbfb8aa3b, v126
	v_exp_f32_e32 v134, v134
	v_cvt_pk_bf16_f32 v124, v124, v125
	v_add_f32_e32 v134, 1.0, v134
	v_rcp_f32_e32 v134, v134
	s_nop 0
	v_cndmask_b32_e32 v126, v126, v134, vcc
	v_mul_f32_e32 v134, 0xbfb8aa3b, v127
	v_exp_f32_e32 v134, v134
	s_nop 0
	v_add_f32_e32 v134, 1.0, v134
	v_rcp_f32_e32 v134, v134
	s_nop 0
	v_cndmask_b32_e32 v127, v127, v134, vcc
	v_cvt_pk_bf16_f32 v125, v126, v127
	v_mul_f32_e32 v126, 0xbfb8aa3b, v120
	v_exp_f32_e32 v126, v126
	s_nop 0
	v_add_f32_e32 v126, 1.0, v126
	v_rcp_f32_e32 v126, v126
	s_nop 0
	v_cndmask_b32_e32 v120, v120, v126, vcc
	v_mul_f32_e32 v126, 0xbfb8aa3b, v121
	v_exp_f32_e32 v126, v126
	s_nop 0
	v_add_f32_e32 v126, 1.0, v126
	v_rcp_f32_e32 v126, v126
	s_nop 0
	v_cndmask_b32_e32 v121, v121, v126, vcc
	v_mul_f32_e32 v126, 0xbfb8aa3b, v122
	v_exp_f32_e32 v126, v126
	s_nop 0
	v_add_f32_e32 v126, 1.0, v126
	v_rcp_f32_e32 v126, v126
	s_nop 0
	v_cndmask_b32_e32 v122, v122, v126, vcc
	v_mul_f32_e32 v126, 0xbfb8aa3b, v123
	v_exp_f32_e32 v126, v126
	s_nop 0
	v_add_f32_e32 v126, 1.0, v126
	v_rcp_f32_e32 v126, v126
	s_nop 0
	v_cndmask_b32_e32 v123, v123, v126, vcc
	v_cvt_pk_bf16_f32 v126, v120, v121
	v_cvt_pk_bf16_f32 v127, v122, v123
	v_mad_i64_i32 v[120:121], s[6:7], s12, v130, 0
	v_permlane16_swap_b32_e32 v124, v126
	v_permlane16_swap_b32_e32 v125, v127
	v_lshl_add_u64 v[120:121], v[120:121], 1, v[128:129]
	global_store_dwordx4 v[120:121], v[124:127], off
	v_mul_f32_e32 v120, s29, v133
	v_mul_f32_e32 v116, v116, v120
	v_mul_f32_e32 v122, 0xbfb8aa3b, v116
	v_exp_f32_e32 v122, v122
	v_mul_f32_e32 v117, v117, v120
	v_mul_f32_e32 v118, v118, v120
	v_mul_f32_e32 v119, v119, v120
	v_add_f32_e32 v122, 1.0, v122
	v_rcp_f32_e32 v122, v122
	v_mul_f32_e32 v112, v112, v120
	v_mul_f32_e32 v113, v113, v120
	v_mul_f32_e32 v114, v114, v120
	v_cndmask_b32_e32 v116, v116, v122, vcc
	v_mul_f32_e32 v122, 0xbfb8aa3b, v117
	v_exp_f32_e32 v122, v122
	v_mul_f32_e32 v115, v115, v120
	v_add_u32_e32 v121, 16, v130
	v_add_f32_e32 v122, 1.0, v122
	v_rcp_f32_e32 v122, v122
	s_nop 0
	v_cndmask_b32_e32 v117, v117, v122, vcc
	v_mul_f32_e32 v122, 0xbfb8aa3b, v118
	v_exp_f32_e32 v122, v122
	v_cvt_pk_bf16_f32 v116, v116, v117
	v_add_f32_e32 v122, 1.0, v122
	v_rcp_f32_e32 v122, v122
	s_nop 0
	v_cndmask_b32_e32 v118, v118, v122, vcc
	v_mul_f32_e32 v122, 0xbfb8aa3b, v119
	v_exp_f32_e32 v122, v122
	s_nop 0
	v_add_f32_e32 v122, 1.0, v122
	v_rcp_f32_e32 v122, v122
	s_nop 0
	v_cndmask_b32_e32 v119, v119, v122, vcc
	v_cvt_pk_bf16_f32 v117, v118, v119
	v_mul_f32_e32 v118, 0xbfb8aa3b, v112
	v_exp_f32_e32 v118, v118
	s_nop 0
	v_add_f32_e32 v118, 1.0, v118
	v_rcp_f32_e32 v118, v118
	s_nop 0
	v_cndmask_b32_e32 v112, v112, v118, vcc
	v_mul_f32_e32 v118, 0xbfb8aa3b, v113
	v_exp_f32_e32 v118, v118
	s_nop 0
	v_add_f32_e32 v118, 1.0, v118
	v_rcp_f32_e32 v118, v118
	s_nop 0
	v_cndmask_b32_e32 v113, v113, v118, vcc
	v_mul_f32_e32 v118, 0xbfb8aa3b, v114
	v_exp_f32_e32 v118, v118
	s_nop 0
	v_add_f32_e32 v118, 1.0, v118
	v_rcp_f32_e32 v118, v118
	s_nop 0
	v_cndmask_b32_e32 v114, v114, v118, vcc
	v_mul_f32_e32 v118, 0xbfb8aa3b, v115
	v_exp_f32_e32 v118, v118
	s_nop 0
	v_add_f32_e32 v118, 1.0, v118
	v_rcp_f32_e32 v118, v118
	s_nop 0
	v_cndmask_b32_e32 v115, v115, v118, vcc
	v_cvt_pk_bf16_f32 v118, v112, v113
	v_cvt_pk_bf16_f32 v119, v114, v115
	v_mad_i64_i32 v[112:113], s[6:7], s12, v121, 0
	v_permlane16_swap_b32_e32 v116, v118
	v_permlane16_swap_b32_e32 v117, v119
	v_lshl_add_u64 v[112:113], v[112:113], 1, v[128:129]
	global_store_dwordx4 v[112:113], v[116:119], off
	ds_read2_b32 v[112:113], v131 offset0:32 offset1:48
	v_add_u32_e32 v114, 32, v130
	s_waitcnt lgkmcnt(0)
; template <int EPI, int MB, int NB> ...
;     ...
;     const int region = bcol >> 10;
;     size_t doff; int ld, cb; bool sig = false;
;     if (region == 0) { doff = OFF_Q; ld = 1024; cb = 0; }
;     else if (region == 1) { doff = OFF_K; ld = 1024; cb = 1024; }
;     else if (region == 3) { doff = OFF_PIN; ld = 1024; cb = 3072; }
;     else if (region < 6) { doff = OFF_SGA; ld = 2048; cb = 4096; sig = true; }
;     else { doff = OFF_SGP; ld = 2048; cb = 6144; sig = true; }
;     ...
; #pragma unroll
;     for (int m = 0; m < MB; ++m) {
;       const int lr = lrow0 + m * 16;
;       const float rs = s_rstd[lr] * qs;
;       u16* orow = dst + (size_t)(brow + lr) * ld + (col0 - cb);
;       u32x2 ob[2];
; #pragma unroll
;       for (int n = 0; n < NB; ++n) {
;         float v[4];
; #pragma unroll
;         for (int j = 0; j < 4; ++j) { v[j] = acc[m][n][j] * rs; if (sig) v[j] = __builtin_amdgcn_rcpf(1.f + __expf(-v[j])); }
;         ob[n][0] = pk_bf16(v[0], v[1]); ob[n][1] = pk_bf16(v[2], v[3]);
;       }
;       *(i32x4*)(orow + wofs) = widen16(ob[0], ob[1]);
;     }
	v_mul_f32_e32 v112, s29, v112
	v_mul_f32_e32 v108, v108, v112
	v_mul_f32_e32 v115, 0xbfb8aa3b, v108
	v_exp_f32_e32 v115, v115
	v_mul_f32_e32 v109, v109, v112
	v_mul_f32_e32 v110, v110, v112
	v_mul_f32_e32 v111, v111, v112
	v_add_f32_e32 v115, 1.0, v115
	v_rcp_f32_e32 v115, v115
	v_mul_f32_e32 v104, v104, v112
	v_mul_f32_e32 v105, v105, v112
	v_mul_f32_e32 v106, v106, v112
	v_cndmask_b32_e32 v108, v108, v115, vcc
	v_mul_f32_e32 v115, 0xbfb8aa3b, v109
	v_exp_f32_e32 v115, v115
	v_mul_f32_e32 v107, v107, v112
	v_add_f32_e32 v115, 1.0, v115
	v_rcp_f32_e32 v115, v115
	s_nop 0
	v_cndmask_b32_e32 v109, v109, v115, vcc
	v_mul_f32_e32 v115, 0xbfb8aa3b, v110
	v_exp_f32_e32 v115, v115
	v_cvt_pk_bf16_f32 v108, v108, v109
	v_add_f32_e32 v115, 1.0, v115
	v_rcp_f32_e32 v115, v115
	s_nop 0
	v_cndmask_b32_e32 v110, v110, v115, vcc
	v_mul_f32_e32 v115, 0xbfb8aa3b, v111
	v_exp_f32_e32 v115, v115
	s_nop 0
	v_add_f32_e32 v115, 1.0, v115
	v_rcp_f32_e32 v115, v115
	s_nop 0
	v_cndmask_b32_e32 v111, v111, v115, vcc
	v_cvt_pk_bf16_f32 v109, v110, v111
	v_mul_f32_e32 v110, 0xbfb8aa3b, v104
	v_exp_f32_e32 v110, v110
	s_nop 0
	v_add_f32_e32 v110, 1.0, v110
	v_rcp_f32_e32 v110, v110
	s_nop 0
	v_cndmask_b32_e32 v104, v104, v110, vcc
	v_mul_f32_e32 v110, 0xbfb8aa3b, v105
	v_exp_f32_e32 v110, v110
	s_nop 0
	v_add_f32_e32 v110, 1.0, v110
	v_rcp_f32_e32 v110, v110
	s_nop 0
	v_cndmask_b32_e32 v105, v105, v110, vcc
	v_mul_f32_e32 v110, 0xbfb8aa3b, v106
	v_exp_f32_e32 v110, v110
	s_nop 0
	v_add_f32_e32 v110, 1.0, v110
	v_rcp_f32_e32 v110, v110
	s_nop 0
	v_cndmask_b32_e32 v106, v106, v110, vcc
	v_mul_f32_e32 v110, 0xbfb8aa3b, v107
	v_exp_f32_e32 v110, v110
	s_nop 0
	v_add_f32_e32 v110, 1.0, v110
	v_rcp_f32_e32 v110, v110
	s_nop 0
	v_cndmask_b32_e32 v107, v107, v110, vcc
	v_cvt_pk_bf16_f32 v110, v104, v105
	v_cvt_pk_bf16_f32 v111, v106, v107
	v_mad_i64_i32 v[104:105], s[6:7], s12, v114, 0
	v_permlane16_swap_b32_e32 v108, v110
	v_permlane16_swap_b32_e32 v109, v111
	v_lshl_add_u64 v[104:105], v[104:105], 1, v[128:129]
	global_store_dwordx4 v[104:105], v[108:111], off
	v_mul_f32_e32 v104, s29, v113
	v_mul_f32_e32 v100, v100, v104
	v_mul_f32_e32 v106, 0xbfb8aa3b, v100
	v_exp_f32_e32 v106, v106
	v_mul_f32_e32 v101, v101, v104
	v_mul_f32_e32 v102, v102, v104
	v_mul_f32_e32 v103, v103, v104
	v_add_f32_e32 v106, 1.0, v106
	v_rcp_f32_e32 v106, v106
	v_mul_f32_e32 v96, v96, v104
	v_mul_f32_e32 v97, v97, v104
	v_mul_f32_e32 v98, v98, v104
	v_cndmask_b32_e32 v100, v100, v106, vcc
	v_mul_f32_e32 v106, 0xbfb8aa3b, v101
	v_exp_f32_e32 v106, v106
	v_mul_f32_e32 v99, v99, v104
	v_add_u32_e32 v105, 48, v130
	v_add_f32_e32 v106, 1.0, v106
	v_rcp_f32_e32 v106, v106
	s_nop 0
	v_cndmask_b32_e32 v101, v101, v106, vcc
	v_mul_f32_e32 v106, 0xbfb8aa3b, v102
	v_exp_f32_e32 v106, v106
	v_cvt_pk_bf16_f32 v100, v100, v101
	v_add_f32_e32 v106, 1.0, v106
	v_rcp_f32_e32 v106, v106
	s_nop 0
	v_cndmask_b32_e32 v102, v102, v106, vcc
	v_mul_f32_e32 v106, 0xbfb8aa3b, v103
	v_exp_f32_e32 v106, v106
	s_nop 0
	v_add_f32_e32 v106, 1.0, v106
	v_rcp_f32_e32 v106, v106
	s_nop 0
	v_cndmask_b32_e32 v103, v103, v106, vcc
	v_cvt_pk_bf16_f32 v101, v102, v103
	v_mul_f32_e32 v102, 0xbfb8aa3b, v96
	v_exp_f32_e32 v102, v102
	s_nop 0
	v_add_f32_e32 v102, 1.0, v102
	v_rcp_f32_e32 v102, v102
	s_nop 0
	v_cndmask_b32_e32 v96, v96, v102, vcc
	v_mul_f32_e32 v102, 0xbfb8aa3b, v97
	v_exp_f32_e32 v102, v102
	s_nop 0
	v_add_f32_e32 v102, 1.0, v102
	v_rcp_f32_e32 v102, v102
	s_nop 0
	v_cndmask_b32_e32 v97, v97, v102, vcc
	v_mul_f32_e32 v102, 0xbfb8aa3b, v98
	v_exp_f32_e32 v102, v102
	s_nop 0
	v_add_f32_e32 v102, 1.0, v102
	v_rcp_f32_e32 v102, v102
	s_nop 0
	v_cndmask_b32_e32 v98, v98, v102, vcc
	v_mul_f32_e32 v102, 0xbfb8aa3b, v99
	v_exp_f32_e32 v102, v102
	s_nop 0
	v_add_f32_e32 v102, 1.0, v102
	v_rcp_f32_e32 v102, v102
	s_nop 0
	v_cndmask_b32_e32 v99, v99, v102, vcc
	v_cvt_pk_bf16_f32 v102, v96, v97
	v_cvt_pk_bf16_f32 v103, v98, v99
	v_mad_i64_i32 v[96:97], s[6:7], s12, v105, 0
	v_permlane16_swap_b32_e32 v100, v102
	v_permlane16_swap_b32_e32 v101, v103
	v_lshl_add_u64 v[96:97], v[96:97], 1, v[128:129]
	global_store_dwordx4 v[96:97], v[100:103], off
.Lwin_join_1:
	v_cndmask_b32_e64 v97, 0, 1, s[8:9]
	v_mov_b32_e32 v98, v212
	v_mov_b32_e32 v96, v214
	v_cmp_ne_u32_e64 s[12:13], 1, v97
	s_andn2_b64 vcc, exec, s[8:9]
	s_cbranch_vccnz .LBB0_225
	s_cmp_lt_i32 s25, 3
	s_cbranch_scc1 .LBB0_226
	s_cmp_eq_u32 s25, 3
	s_mov_b64 s[8:9], -1
	s_cbranch_scc0 .LBB0_222
	s_mov_b64 s[8:9], 0

; template <int EPI, int MB, int NB> ...
;     ...
;     u16* dst = (u16*)(e.wsb + doff);
;     const float qs = region == 0 ? QSCALE : 1.f;
; #pragma unroll
;     for (int m = 0; m < MB; ++m) {
;       const int lr = lrow0 + m * 16;
;       const float rs = s_rstd[lr] * qs;
;       u16* orow = dst + (size_t)(brow + lr) * ld + (col0 - cb);
;       u32x2 ob[2];
; #pragma unroll
;       for (int n = 0; n < NB; ++n) {
;         float v[4];
; #pragma unroll
;         for (int j = 0; j < 4; ++j) { v[j] = acc[m][n][j] * rs; if (sig) v[j] = __builtin_amdgcn_rcpf(1.f + __expf(-v[j])); }
;         ob[n][0] = pk_bf16(v[0], v[1]); ob[n][1] = pk_bf16(v[2], v[3]);
;       }
;       *(i32x4*)(orow + wofs) = widen16(ob[0], ob[1]);
;     }
.LBB0_230:
	s_cmp_eq_u64 s[8:9], 0
	s_cbranch_scc1 .Lwin_fast_2
	v_lshl_add_u32 v99, v98, 2, s19
	ds_read2_b32 v[100:101], v99 offset1:16
	s_add_u32 s6, s56, s6
	s_addc_u32 s7, s57, s7
	s_add_i32 s23, s23, s24
	v_add_u32_e32 v96, s23, v96
	s_waitcnt lgkmcnt(0)
	v_mul_f32_e32 v100, s29, v100
	v_mul_f32_e32 v92, v92, v100
	v_mul_f32_e32 v102, 0xbfb8aa3b, v92
	v_exp_f32_e32 v102, v102
	v_mul_f32_e32 v93, v93, v100
	v_mul_f32_e32 v94, v94, v100
	v_mul_f32_e32 v95, v95, v100
	v_add_f32_e32 v102, 1.0, v102
	v_rcp_f32_e32 v102, v102
	v_mul_f32_e32 v88, v88, v100
	v_mul_f32_e32 v89, v89, v100
	v_mul_f32_e32 v90, v90, v100
	v_cndmask_b32_e64 v92, v92, v102, s[8:9]
	v_mul_f32_e32 v102, 0xbfb8aa3b, v93
	v_exp_f32_e32 v102, v102
	v_mul_f32_e32 v91, v91, v100
	v_ashrrev_i32_e32 v97, 31, v96
	v_lshl_add_u64 v[96:97], v[96:97], 1, s[6:7]
	v_add_f32_e32 v102, 1.0, v102
	v_rcp_f32_e32 v102, v102
	v_add_u32_e32 v98, s28, v98
	v_lshl_add_u64 v[96:97], v[194:195], 1, v[96:97]
	v_cndmask_b32_e64 v93, v93, v102, s[8:9]
	v_mul_f32_e32 v102, 0xbfb8aa3b, v94
	v_exp_f32_e32 v102, v102
	v_cvt_pk_bf16_f32 v92, v92, v93
	v_add_f32_e32 v102, 1.0, v102
	v_rcp_f32_e32 v102, v102
	s_nop 0
	v_cndmask_b32_e64 v94, v94, v102, s[8:9]
	v_mul_f32_e32 v102, 0xbfb8aa3b, v95
	v_exp_f32_e32 v102, v102
	s_nop 0
	v_add_f32_e32 v102, 1.0, v102
	v_rcp_f32_e32 v102, v102
	s_nop 0
	v_cndmask_b32_e64 v95, v95, v102, s[8:9]
	v_cvt_pk_bf16_f32 v93, v94, v95
	v_mul_f32_e32 v94, 0xbfb8aa3b, v88
	v_exp_f32_e32 v94, v94
	s_nop 0
	v_add_f32_e32 v94, 1.0, v94
	v_rcp_f32_e32 v94, v94
	s_nop 0
	v_cndmask_b32_e64 v88, v88, v94, s[8:9]
	v_mul_f32_e32 v94, 0xbfb8aa3b, v89
	v_exp_f32_e32 v94, v94
	s_nop 0
	v_add_f32_e32 v94, 1.0, v94
	v_rcp_f32_e32 v94, v94
	s_nop 0
	v_cndmask_b32_e64 v89, v89, v94, s[8:9]
	v_mul_f32_e32 v94, 0xbfb8aa3b, v90
	v_exp_f32_e32 v94, v94
	s_nop 0
	v_add_f32_e32 v94, 1.0, v94
	v_rcp_f32_e32 v94, v94
	s_nop 0
	v_cndmask_b32_e64 v90, v90, v94, s[8:9]
	v_mul_f32_e32 v94, 0xbfb8aa3b, v91
	v_exp_f32_e32 v94, v94
	s_nop 0
	v_add_f32_e32 v94, 1.0, v94
	v_rcp_f32_e32 v94, v94
	s_nop 0
	v_cndmask_b32_e64 v91, v91, v94, s[8:9]
	v_cvt_pk_bf16_f32 v94, v88, v89
	v_cvt_pk_bf16_f32 v95, v90, v91
	v_mad_i64_i32 v[88:89], s[6:7], vcc_lo, v98, 0
	v_permlane16_swap_b32_e32 v92, v94
	v_permlane16_swap_b32_e32 v93, v95
	v_lshl_add_u64 v[88:89], v[88:89], 1, v[96:97]
	global_store_dwordx4 v[88:89], v[92:95], off
	v_mul_f32_e32 v88, s29, v101
	v_mul_f32_e32 v84, v84, v88
	v_mul_f32_e32 v90, 0xbfb8aa3b, v84
	v_exp_f32_e32 v90, v90
	v_mul_f32_e32 v85, v85, v88
	v_mul_f32_e32 v86, v86, v88
	v_mul_f32_e32 v87, v87, v88
	v_add_f32_e32 v90, 1.0, v90
	v_rcp_f32_e32 v90, v90
	v_mul_f32_e32 v80, v80, v88
	v_mul_f32_e32 v81, v81, v88
	v_mul_f32_e32 v82, v82, v88
	v_cndmask_b32_e64 v84, v84, v90, s[8:9]
	v_mul_f32_e32 v90, 0xbfb8aa3b, v85
	v_exp_f32_e32 v90, v90
	v_mul_f32_e32 v83, v83, v88
	v_add_u32_e32 v89, 16, v98
	v_add_f32_e32 v90, 1.0, v90
	v_rcp_f32_e32 v90, v90
	s_nop 0
	v_cndmask_b32_e64 v85, v85, v90, s[8:9]
	v_mul_f32_e32 v90, 0xbfb8aa3b, v86
	v_exp_f32_e32 v90, v90
	v_cvt_pk_bf16_f32 v84, v84, v85
	v_add_f32_e32 v90, 1.0, v90
	v_rcp_f32_e32 v90, v90
	s_nop 0
	v_cndmask_b32_e64 v86, v86, v90, s[8:9]
	v_mul_f32_e32 v90, 0xbfb8aa3b, v87
	v_exp_f32_e32 v90, v90
	s_nop 0
	v_add_f32_e32 v90, 1.0, v90
	v_rcp_f32_e32 v90, v90
	s_nop 0
	v_cndmask_b32_e64 v87, v87, v90, s[8:9]
	v_cvt_pk_bf16_f32 v85, v86, v87
	v_mul_f32_e32 v86, 0xbfb8aa3b, v80
	v_exp_f32_e32 v86, v86
	s_nop 0
	v_add_f32_e32 v86, 1.0, v86
	v_rcp_f32_e32 v86, v86
	s_nop 0
	v_cndmask_b32_e64 v80, v80, v86, s[8:9]
	v_mul_f32_e32 v86, 0xbfb8aa3b, v81
	v_exp_f32_e32 v86, v86
	s_nop 0
	v_add_f32_e32 v86, 1.0, v86
	v_rcp_f32_e32 v86, v86
	s_nop 0
	v_cndmask_b32_e64 v81, v81, v86, s[8:9]
	v_mul_f32_e32 v86, 0xbfb8aa3b, v82
	v_exp_f32_e32 v86, v86
	s_nop 0
	v_add_f32_e32 v86, 1.0, v86
	v_rcp_f32_e32 v86, v86
	s_nop 0
	v_cndmask_b32_e64 v82, v82, v86, s[8:9]
	v_mul_f32_e32 v86, 0xbfb8aa3b, v83
	v_exp_f32_e32 v86, v86
	s_nop 0
	v_add_f32_e32 v86, 1.0, v86
	v_rcp_f32_e32 v86, v86
	s_nop 0
	v_cndmask_b32_e64 v83, v83, v86, s[8:9]
	v_cvt_pk_bf16_f32 v86, v80, v81
	v_cvt_pk_bf16_f32 v87, v82, v83
	v_mad_i64_i32 v[80:81], s[6:7], vcc_lo, v89, 0
	v_permlane16_swap_b32_e32 v84, v86
	v_permlane16_swap_b32_e32 v85, v87
	v_lshl_add_u64 v[80:81], v[80:81], 1, v[96:97]
	global_store_dwordx4 v[80:81], v[84:87], off
	ds_read2_b32 v[80:81], v99 offset0:32 offset1:48
	v_add_u32_e32 v82, 32, v98
	s_waitcnt lgkmcnt(0)
; template <int EPI, int MB, int NB> ...
;     ...
;     const int region = bcol >> 10;
;     size_t doff; int ld, cb; bool sig = false;
;     if (region == 0) { doff = OFF_Q; ld = 1024; cb = 0; }
;     else if (region == 1) { doff = OFF_K; ld = 1024; cb = 1024; }
;     else if (region == 3) { doff = OFF_PIN; ld = 1024; cb = 3072; }
;     else if (region < 6) { doff = OFF_SGA; ld = 2048; cb = 4096; sig = true; }
;     else { doff = OFF_SGP; ld = 2048; cb = 6144; sig = true; }
;     u16* dst = (u16*)(e.wsb + doff);
;     const float qs = region == 0 ? QSCALE : 1.f;
; #pragma unroll
;     for (int m = 0; m < MB; ++m) {
;       const int lr = lrow0 + m * 16;
;       const float rs = s_rstd[lr] * qs;
;       u16* orow = dst + (size_t)(brow + lr) * ld + (col0 - cb);
;       u32x2 ob[2];
; #pragma unroll
;       for (int n = 0; n < NB; ++n) {
;         float v[4];
; #pragma unroll
;         for (int j = 0; j < 4; ++j) { v[j] = acc[m][n][j] * rs; if (sig) v[j] = __builtin_amdgcn_rcpf(1.f + __expf(-v[j])); }
;         ob[n][0] = pk_bf16(v[0], v[1]); ob[n][1] = pk_bf16(v[2], v[3]);
;       }
;       *(i32x4*)(orow + wofs) = widen16(ob[0], ob[1]);
;     }
	v_mul_f32_e32 v80, s29, v80
	v_mul_f32_e32 v76, v76, v80
	v_mul_f32_e32 v83, 0xbfb8aa3b, v76
	v_exp_f32_e32 v83, v83
	v_mul_f32_e32 v77, v77, v80
	v_mul_f32_e32 v78, v78, v80
	v_mul_f32_e32 v79, v79, v80
	v_add_f32_e32 v83, 1.0, v83
	v_rcp_f32_e32 v83, v83
	v_mul_f32_e32 v72, v72, v80
	v_mul_f32_e32 v73, v73, v80
	v_mul_f32_e32 v74, v74, v80
	v_cndmask_b32_e64 v76, v76, v83, s[8:9]
	v_mul_f32_e32 v83, 0xbfb8aa3b, v77
	v_exp_f32_e32 v83, v83
	v_mul_f32_e32 v75, v75, v80
	v_add_f32_e32 v83, 1.0, v83
	v_rcp_f32_e32 v83, v83
	s_nop 0
	v_cndmask_b32_e64 v77, v77, v83, s[8:9]
	v_mul_f32_e32 v83, 0xbfb8aa3b, v78
	v_exp_f32_e32 v83, v83
	v_cvt_pk_bf16_f32 v76, v76, v77
	v_add_f32_e32 v83, 1.0, v83
	v_rcp_f32_e32 v83, v83
	s_nop 0
	v_cndmask_b32_e64 v78, v78, v83, s[8:9]
	v_mul_f32_e32 v83, 0xbfb8aa3b, v79
	v_exp_f32_e32 v83, v83
	s_nop 0
	v_add_f32_e32 v83, 1.0, v83
	v_rcp_f32_e32 v83, v83
	s_nop 0
	v_cndmask_b32_e64 v79, v79, v83, s[8:9]
	v_cvt_pk_bf16_f32 v77, v78, v79
	v_mul_f32_e32 v78, 0xbfb8aa3b, v72
	v_exp_f32_e32 v78, v78
	s_nop 0
	v_add_f32_e32 v78, 1.0, v78
	v_rcp_f32_e32 v78, v78
	s_nop 0
	v_cndmask_b32_e64 v72, v72, v78, s[8:9]
	v_mul_f32_e32 v78, 0xbfb8aa3b, v73
	v_exp_f32_e32 v78, v78
	s_nop 0
	v_add_f32_e32 v78, 1.0, v78
	v_rcp_f32_e32 v78, v78
	s_nop 0
	v_cndmask_b32_e64 v73, v73, v78, s[8:9]
	v_mul_f32_e32 v78, 0xbfb8aa3b, v74
	v_exp_f32_e32 v78, v78
	s_nop 0
	v_add_f32_e32 v78, 1.0, v78
	v_rcp_f32_e32 v78, v78
	s_nop 0
	v_cndmask_b32_e64 v74, v74, v78, s[8:9]
	v_mul_f32_e32 v78, 0xbfb8aa3b, v75
	v_exp_f32_e32 v78, v78
	s_nop 0
	v_add_f32_e32 v78, 1.0, v78
	v_rcp_f32_e32 v78, v78
	s_nop 0
	v_cndmask_b32_e64 v75, v75, v78, s[8:9]
	v_cvt_pk_bf16_f32 v78, v72, v73
	v_cvt_pk_bf16_f32 v79, v74, v75
	v_mad_i64_i32 v[72:73], s[6:7], vcc_lo, v82, 0
	v_permlane16_swap_b32_e32 v76, v78
	v_permlane16_swap_b32_e32 v77, v79
	v_lshl_add_u64 v[72:73], v[72:73], 1, v[96:97]
	global_store_dwordx4 v[72:73], v[76:79], off
	v_mul_f32_e32 v72, s29, v81
	v_mul_f32_e32 v68, v68, v72
	v_mul_f32_e32 v74, 0xbfb8aa3b, v68
	v_exp_f32_e32 v74, v74
	v_mul_f32_e32 v69, v69, v72
	v_mul_f32_e32 v70, v70, v72
	v_mul_f32_e32 v71, v71, v72
	v_add_f32_e32 v74, 1.0, v74
	v_rcp_f32_e32 v74, v74
	v_mul_f32_e32 v64, v64, v72
	v_mul_f32_e32 v65, v65, v72
	v_mul_f32_e32 v66, v66, v72
	v_cndmask_b32_e64 v68, v68, v74, s[8:9]
	v_mul_f32_e32 v74, 0xbfb8aa3b, v69
	v_exp_f32_e32 v74, v74
	v_mul_f32_e32 v67, v67, v72
	v_add_u32_e32 v73, 48, v98
	v_add_f32_e32 v74, 1.0, v74
	v_rcp_f32_e32 v74, v74
	s_nop 0
	v_cndmask_b32_e64 v69, v69, v74, s[8:9]
	v_mul_f32_e32 v74, 0xbfb8aa3b, v70
	v_exp_f32_e32 v74, v74
	v_cvt_pk_bf16_f32 v68, v68, v69
	v_add_f32_e32 v74, 1.0, v74
	v_rcp_f32_e32 v74, v74
	s_nop 0
	v_cndmask_b32_e64 v70, v70, v74, s[8:9]
	v_mul_f32_e32 v74, 0xbfb8aa3b, v71
	v_exp_f32_e32 v74, v74
	s_nop 0
	v_add_f32_e32 v74, 1.0, v74
	v_rcp_f32_e32 v74, v74
	s_nop 0
	v_cndmask_b32_e64 v71, v71, v74, s[8:9]
	v_cvt_pk_bf16_f32 v69, v70, v71
	v_mul_f32_e32 v70, 0xbfb8aa3b, v64
	v_exp_f32_e32 v70, v70
	s_nop 0
	v_add_f32_e32 v70, 1.0, v70
	v_rcp_f32_e32 v70, v70
	s_nop 0
	v_cndmask_b32_e64 v64, v64, v70, s[8:9]
	v_mul_f32_e32 v70, 0xbfb8aa3b, v65
	v_exp_f32_e32 v70, v70
	s_nop 0
	v_add_f32_e32 v70, 1.0, v70
	v_rcp_f32_e32 v70, v70
	s_nop 0
	v_cndmask_b32_e64 v65, v65, v70, s[8:9]
	v_mul_f32_e32 v70, 0xbfb8aa3b, v66
	v_exp_f32_e32 v70, v70
	s_nop 0
	v_add_f32_e32 v70, 1.0, v70
	v_rcp_f32_e32 v70, v70
	s_nop 0
	v_cndmask_b32_e64 v66, v66, v70, s[8:9]
	v_mul_f32_e32 v70, 0xbfb8aa3b, v67
	v_exp_f32_e32 v70, v70
	s_nop 0
	v_add_f32_e32 v70, 1.0, v70
	v_rcp_f32_e32 v70, v70
	s_nop 0
	v_cndmask_b32_e64 v67, v67, v70, s[8:9]
	v_cvt_pk_bf16_f32 v70, v64, v65
	v_cvt_pk_bf16_f32 v71, v66, v67
	v_mad_i64_i32 v[64:65], s[6:7], vcc_lo, v73, 0
	v_permlane16_swap_b32_e32 v68, v70
	v_permlane16_swap_b32_e32 v69, v71
	v_lshl_add_u64 v[64:65], v[64:65], 1, v[96:97]
	global_store_dwordx4 v[64:65], v[68:71], off
.Lwin_join_2:
	v_mov_b32_e32 v66, v215
	v_mov_b32_e32 v64, v213
	s_and_b64 vcc, exec, s[12:13]
	s_cbranch_vccnz .LBB0_237
	s_cmp_lt_i32 s25, 3
	s_cbranch_scc1 .LBB0_238
	s_cmp_eq_u32 s25, 3
	s_mov_b64 s[8:9], -1
	s_cbranch_scc0 .LBB0_234
	s_mov_b64 s[8:9], 0

; template <int EPI, int MB, int NB> ...
;     ...
; #pragma unroll
;     for (int m = 0; m < MB; ++m) {
;       const int lr = lrow0 + m * 16;
;       const float rs = s_rstd[lr] * qs;
;       u16* orow = dst + (size_t)(brow + lr) * ld + (col0 - cb);
;       u32x2 ob[2];
; #pragma unroll
;       for (int n = 0; n < NB; ++n) {
;         float v[4];
; #pragma unroll
;         for (int j = 0; j < 4; ++j) { v[j] = acc[m][n][j] * rs; if (sig) v[j] = __builtin_amdgcn_rcpf(1.f + __expf(-v[j])); }
;         ob[n][0] = pk_bf16(v[0], v[1]); ob[n][1] = pk_bf16(v[2], v[3]);
;       }
;       *(i32x4*)(orow + wofs) = widen16(ob[0], ob[1]);
;     }
.LBB0_242:
	s_cmp_eq_u64 s[8:9], 0
	s_cbranch_scc1 .Lwin_fast_3
	v_lshl_add_u32 v67, v66, 2, s19
	ds_read2_b32 v[68:69], v67 offset1:16
	s_add_u32 s6, s56, s6
	s_addc_u32 s7, s57, s7
	s_add_i32 s23, s23, s24
	v_add_u32_e32 v64, s23, v64
	s_waitcnt lgkmcnt(0)
	v_mul_f32_e32 v68, s29, v68
	v_mul_f32_e32 v60, v60, v68
	v_mul_f32_e32 v70, 0xbfb8aa3b, v60
	v_exp_f32_e32 v70, v70
	v_mul_f32_e32 v61, v61, v68
	v_mul_f32_e32 v62, v62, v68
	v_mul_f32_e32 v63, v63, v68
	v_add_f32_e32 v70, 1.0, v70
	v_rcp_f32_e32 v70, v70
	v_mul_f32_e32 v56, v56, v68
	v_mul_f32_e32 v57, v57, v68
	v_mul_f32_e32 v58, v58, v68
	v_cndmask_b32_e64 v60, v60, v70, s[8:9]
	v_mul_f32_e32 v70, 0xbfb8aa3b, v61
	v_exp_f32_e32 v70, v70
	v_mul_f32_e32 v59, v59, v68
	v_ashrrev_i32_e32 v65, 31, v64
	v_lshl_add_u64 v[64:65], v[64:65], 1, s[6:7]
	v_add_f32_e32 v70, 1.0, v70
	v_rcp_f32_e32 v70, v70
	v_add_u32_e32 v66, s28, v66
	v_lshl_add_u64 v[64:65], v[194:195], 1, v[64:65]
	v_cndmask_b32_e64 v61, v61, v70, s[8:9]
	v_mul_f32_e32 v70, 0xbfb8aa3b, v62
	v_exp_f32_e32 v70, v70
	v_cvt_pk_bf16_f32 v60, v60, v61
	v_add_f32_e32 v70, 1.0, v70
	v_rcp_f32_e32 v70, v70
	s_nop 0
	v_cndmask_b32_e64 v62, v62, v70, s[8:9]
	v_mul_f32_e32 v70, 0xbfb8aa3b, v63
	v_exp_f32_e32 v70, v70
	s_nop 0
	v_add_f32_e32 v70, 1.0, v70
	v_rcp_f32_e32 v70, v70
	s_nop 0
	v_cndmask_b32_e64 v63, v63, v70, s[8:9]
	v_cvt_pk_bf16_f32 v61, v62, v63
	v_mul_f32_e32 v62, 0xbfb8aa3b, v56
	v_exp_f32_e32 v62, v62
	s_nop 0
	v_add_f32_e32 v62, 1.0, v62
	v_rcp_f32_e32 v62, v62
	s_nop 0
	v_cndmask_b32_e64 v56, v56, v62, s[8:9]
	v_mul_f32_e32 v62, 0xbfb8aa3b, v57
	v_exp_f32_e32 v62, v62
	s_nop 0
	v_add_f32_e32 v62, 1.0, v62
	v_rcp_f32_e32 v62, v62
	s_nop 0
	v_cndmask_b32_e64 v57, v57, v62, s[8:9]
	v_mul_f32_e32 v62, 0xbfb8aa3b, v58
	v_exp_f32_e32 v62, v62
	s_nop 0
	v_add_f32_e32 v62, 1.0, v62
	v_rcp_f32_e32 v62, v62
	s_nop 0
	v_cndmask_b32_e64 v58, v58, v62, s[8:9]
	v_mul_f32_e32 v62, 0xbfb8aa3b, v59
	v_exp_f32_e32 v62, v62
	s_nop 0
	v_add_f32_e32 v62, 1.0, v62
	v_rcp_f32_e32 v62, v62
	s_nop 0
	v_cndmask_b32_e64 v59, v59, v62, s[8:9]
	v_cvt_pk_bf16_f32 v62, v56, v57
	v_cvt_pk_bf16_f32 v63, v58, v59
	v_mad_i64_i32 v[56:57], s[6:7], vcc_lo, v66, 0
	v_permlane16_swap_b32_e32 v60, v62
	v_permlane16_swap_b32_e32 v61, v63
	v_lshl_add_u64 v[56:57], v[56:57], 1, v[64:65]
	global_store_dwordx4 v[56:57], v[60:63], off
	v_mul_f32_e32 v56, s29, v69
	v_mul_f32_e32 v52, v52, v56
	v_mul_f32_e32 v58, 0xbfb8aa3b, v52
	v_exp_f32_e32 v58, v58
	v_mul_f32_e32 v53, v53, v56
	v_mul_f32_e32 v54, v54, v56
	v_mul_f32_e32 v55, v55, v56
	v_add_f32_e32 v58, 1.0, v58
	v_rcp_f32_e32 v58, v58
	v_mul_f32_e32 v48, v48, v56
	v_mul_f32_e32 v49, v49, v56
	v_mul_f32_e32 v50, v50, v56
	v_cndmask_b32_e64 v52, v52, v58, s[8:9]
	v_mul_f32_e32 v58, 0xbfb8aa3b, v53
	v_exp_f32_e32 v58, v58
	v_mul_f32_e32 v51, v51, v56
	v_add_u32_e32 v57, 16, v66
	v_add_f32_e32 v58, 1.0, v58
	v_rcp_f32_e32 v58, v58
	s_nop 0
	v_cndmask_b32_e64 v53, v53, v58, s[8:9]
	v_mul_f32_e32 v58, 0xbfb8aa3b, v54
	v_exp_f32_e32 v58, v58
	v_cvt_pk_bf16_f32 v52, v52, v53
	v_add_f32_e32 v58, 1.0, v58
	v_rcp_f32_e32 v58, v58
	s_nop 0
	v_cndmask_b32_e64 v54, v54, v58, s[8:9]
	v_mul_f32_e32 v58, 0xbfb8aa3b, v55
	v_exp_f32_e32 v58, v58
	s_nop 0
	v_add_f32_e32 v58, 1.0, v58
	v_rcp_f32_e32 v58, v58
	s_nop 0
	v_cndmask_b32_e64 v55, v55, v58, s[8:9]
	v_cvt_pk_bf16_f32 v53, v54, v55
	v_mul_f32_e32 v54, 0xbfb8aa3b, v48
	v_exp_f32_e32 v54, v54
	s_nop 0
	v_add_f32_e32 v54, 1.0, v54
	v_rcp_f32_e32 v54, v54
	s_nop 0
	v_cndmask_b32_e64 v48, v48, v54, s[8:9]
	v_mul_f32_e32 v54, 0xbfb8aa3b, v49
	v_exp_f32_e32 v54, v54
	s_nop 0
	v_add_f32_e32 v54, 1.0, v54
	v_rcp_f32_e32 v54, v54
	s_nop 0
	v_cndmask_b32_e64 v49, v49, v54, s[8:9]
	v_mul_f32_e32 v54, 0xbfb8aa3b, v50
	v_exp_f32_e32 v54, v54
	s_nop 0
	v_add_f32_e32 v54, 1.0, v54
	v_rcp_f32_e32 v54, v54
	s_nop 0
	v_cndmask_b32_e64 v50, v50, v54, s[8:9]
	v_mul_f32_e32 v54, 0xbfb8aa3b, v51
	v_exp_f32_e32 v54, v54
	s_nop 0
	v_add_f32_e32 v54, 1.0, v54
	v_rcp_f32_e32 v54, v54
	s_nop 0
	v_cndmask_b32_e64 v51, v51, v54, s[8:9]
	v_cvt_pk_bf16_f32 v54, v48, v49
	v_cvt_pk_bf16_f32 v55, v50, v51
	v_mad_i64_i32 v[48:49], s[6:7], vcc_lo, v57, 0
	v_permlane16_swap_b32_e32 v52, v54
	v_permlane16_swap_b32_e32 v53, v55
	v_lshl_add_u64 v[48:49], v[48:49], 1, v[64:65]
	global_store_dwordx4 v[48:49], v[52:55], off
	ds_read2_b32 v[48:49], v67 offset0:32 offset1:48
	v_add_u32_e32 v50, 32, v66
	s_waitcnt lgkmcnt(0)
; template <int EPI, int MB, int NB> ...
;     ...
;     const int region = bcol >> 10;
;     size_t doff; int ld, cb; bool sig = false;
;     if (region == 0) { doff = OFF_Q; ld = 1024; cb = 0; }
;     else if (region == 1) { doff = OFF_K; ld = 1024; cb = 1024; }
;     else if (region == 3) { doff = OFF_PIN; ld = 1024; cb = 3072; }
;     else if (region < 6) { doff = OFF_SGA; ld = 2048; cb = 4096; sig = true; }
;     else { doff = OFF_SGP; ld = 2048; cb = 6144; sig = true; }
;     u16* dst = (u16*)(e.wsb + doff);
;     const float qs = region == 0 ? QSCALE : 1.f;
; #pragma unroll
;     for (int m = 0; m < MB; ++m) {
;       const int lr = lrow0 + m * 16;
;       const float rs = s_rstd[lr] * qs;
;       u16* orow = dst + (size_t)(brow + lr) * ld + (col0 - cb);
;       u32x2 ob[2];
; #pragma unroll
;       for (int n = 0; n < NB; ++n) {
;         float v[4];
; #pragma unroll
;         for (int j = 0; j < 4; ++j) { v[j] = acc[m][n][j] * rs; if (sig) v[j] = __builtin_amdgcn_rcpf(1.f + __expf(-v[j])); }
;         ob[n][0] = pk_bf16(v[0], v[1]); ob[n][1] = pk_bf16(v[2], v[3]);
;       }
;       *(i32x4*)(orow + wofs) = widen16(ob[0], ob[1]);
;     }
	v_mul_f32_e32 v48, s29, v48
	v_mul_f32_e32 v44, v44, v48
	v_mul_f32_e32 v51, 0xbfb8aa3b, v44
	v_exp_f32_e32 v51, v51
	v_mul_f32_e32 v45, v45, v48
	v_mul_f32_e32 v46, v46, v48
	v_mul_f32_e32 v47, v47, v48
	v_add_f32_e32 v51, 1.0, v51
	v_rcp_f32_e32 v51, v51
	v_mul_f32_e32 v40, v40, v48
	v_mul_f32_e32 v41, v41, v48
	v_mul_f32_e32 v42, v42, v48
	v_cndmask_b32_e64 v44, v44, v51, s[8:9]
	v_mul_f32_e32 v51, 0xbfb8aa3b, v45
	v_exp_f32_e32 v51, v51
	v_mul_f32_e32 v43, v43, v48
	v_add_f32_e32 v51, 1.0, v51
	v_rcp_f32_e32 v51, v51
	s_nop 0
	v_cndmask_b32_e64 v45, v45, v51, s[8:9]
	v_mul_f32_e32 v51, 0xbfb8aa3b, v46
	v_exp_f32_e32 v51, v51
	v_cvt_pk_bf16_f32 v44, v44, v45
	v_add_f32_e32 v51, 1.0, v51
	v_rcp_f32_e32 v51, v51
	s_nop 0
	v_cndmask_b32_e64 v46, v46, v51, s[8:9]
	v_mul_f32_e32 v51, 0xbfb8aa3b, v47
	v_exp_f32_e32 v51, v51
	s_nop 0
	v_add_f32_e32 v51, 1.0, v51
	v_rcp_f32_e32 v51, v51
	s_nop 0
	v_cndmask_b32_e64 v47, v47, v51, s[8:9]
	v_cvt_pk_bf16_f32 v45, v46, v47
	v_mul_f32_e32 v46, 0xbfb8aa3b, v40
	v_exp_f32_e32 v46, v46
	s_nop 0
	v_add_f32_e32 v46, 1.0, v46
	v_rcp_f32_e32 v46, v46
	s_nop 0
	v_cndmask_b32_e64 v40, v40, v46, s[8:9]
	v_mul_f32_e32 v46, 0xbfb8aa3b, v41
	v_exp_f32_e32 v46, v46
	s_nop 0
	v_add_f32_e32 v46, 1.0, v46
	v_rcp_f32_e32 v46, v46
	s_nop 0
	v_cndmask_b32_e64 v41, v41, v46, s[8:9]
	v_mul_f32_e32 v46, 0xbfb8aa3b, v42
	v_exp_f32_e32 v46, v46
	s_nop 0
	v_add_f32_e32 v46, 1.0, v46
	v_rcp_f32_e32 v46, v46
	s_nop 0
	v_cndmask_b32_e64 v42, v42, v46, s[8:9]
	v_mul_f32_e32 v46, 0xbfb8aa3b, v43
	v_exp_f32_e32 v46, v46
	s_nop 0
	v_add_f32_e32 v46, 1.0, v46
	v_rcp_f32_e32 v46, v46
	s_nop 0
	v_cndmask_b32_e64 v43, v43, v46, s[8:9]
	v_cvt_pk_bf16_f32 v46, v40, v41
	v_cvt_pk_bf16_f32 v47, v42, v43
	v_mad_i64_i32 v[40:41], s[6:7], vcc_lo, v50, 0
	v_permlane16_swap_b32_e32 v44, v46
	v_permlane16_swap_b32_e32 v45, v47
	v_lshl_add_u64 v[40:41], v[40:41], 1, v[64:65]
	global_store_dwordx4 v[40:41], v[44:47], off
	v_mul_f32_e32 v40, s29, v49
	v_mul_f32_e32 v36, v36, v40
	v_mul_f32_e32 v42, 0xbfb8aa3b, v36
	v_exp_f32_e32 v42, v42
	v_mul_f32_e32 v37, v37, v40
	v_mul_f32_e32 v38, v38, v40
	v_mul_f32_e32 v39, v39, v40
	v_add_f32_e32 v42, 1.0, v42
	v_rcp_f32_e32 v42, v42
	v_mul_f32_e32 v32, v32, v40
	v_mul_f32_e32 v33, v33, v40
	v_mul_f32_e32 v34, v34, v40
	v_cndmask_b32_e64 v36, v36, v42, s[8:9]
	v_mul_f32_e32 v42, 0xbfb8aa3b, v37
	v_exp_f32_e32 v42, v42
	v_mul_f32_e32 v35, v35, v40
	v_add_u32_e32 v41, 48, v66
	v_add_f32_e32 v42, 1.0, v42
	v_rcp_f32_e32 v42, v42
	s_nop 0
	v_cndmask_b32_e64 v37, v37, v42, s[8:9]
	v_mul_f32_e32 v42, 0xbfb8aa3b, v38
	v_exp_f32_e32 v42, v42
	v_cvt_pk_bf16_f32 v36, v36, v37
	v_add_f32_e32 v42, 1.0, v42
	v_rcp_f32_e32 v42, v42
	s_nop 0
	v_cndmask_b32_e64 v38, v38, v42, s[8:9]
	v_mul_f32_e32 v42, 0xbfb8aa3b, v39
	v_exp_f32_e32 v42, v42
	s_nop 0
	v_add_f32_e32 v42, 1.0, v42
	v_rcp_f32_e32 v42, v42
	s_nop 0
	v_cndmask_b32_e64 v39, v39, v42, s[8:9]
	v_cvt_pk_bf16_f32 v37, v38, v39
	v_mul_f32_e32 v38, 0xbfb8aa3b, v32
	v_exp_f32_e32 v38, v38
	s_nop 0
	v_add_f32_e32 v38, 1.0, v38
	v_rcp_f32_e32 v38, v38
	s_nop 0
	v_cndmask_b32_e64 v32, v32, v38, s[8:9]
	v_mul_f32_e32 v38, 0xbfb8aa3b, v33
	v_exp_f32_e32 v38, v38
	s_nop 0
	v_add_f32_e32 v38, 1.0, v38
	v_rcp_f32_e32 v38, v38
	s_nop 0
	v_cndmask_b32_e64 v33, v33, v38, s[8:9]
	v_mul_f32_e32 v38, 0xbfb8aa3b, v34
	v_exp_f32_e32 v38, v38
	s_nop 0
	v_add_f32_e32 v38, 1.0, v38
	v_rcp_f32_e32 v38, v38
	s_nop 0
	v_cndmask_b32_e64 v34, v34, v38, s[8:9]
	v_mul_f32_e32 v38, 0xbfb8aa3b, v35
	v_exp_f32_e32 v38, v38
	s_nop 0
	v_add_f32_e32 v38, 1.0, v38
	v_rcp_f32_e32 v38, v38
	s_nop 0
	v_cndmask_b32_e64 v35, v35, v38, s[8:9]
	v_cvt_pk_bf16_f32 v38, v32, v33
	v_cvt_pk_bf16_f32 v39, v34, v35
	v_mad_i64_i32 v[32:33], s[6:7], vcc_lo, v41, 0
	v_permlane16_swap_b32_e32 v36, v38
	v_permlane16_swap_b32_e32 v37, v39
	v_lshl_add_u64 v[32:33], v[32:33], 1, v[64:65]
	global_store_dwordx4 v[32:33], v[36:39], off
.Lwin_join_3:
	v_mov_b32_e32 v34, v215
	v_mov_b32_e32 v32, v214
	s_and_b64 vcc, exec, s[12:13]
	s_cbranch_vccnz .LBB0_249
	s_cmp_lt_i32 s25, 3
	s_cbranch_scc1 .LBB0_250
	s_cmp_eq_u32 s25, 3
	s_mov_b64 s[8:9], -1
	s_cbranch_scc0 .LBB0_246
	s_mov_b64 s[8:9], 0

; template <int EPI, int MB, int NB> ...
;     ...
; #pragma unroll
;     for (int m = 0; m < MB; ++m) {
;       const int lr = lrow0 + m * 16;
;       const float rs = s_rstd[lr] * qs;
;       u16* orow = dst + (size_t)(brow + lr) * ld + (col0 - cb);
;       u32x2 ob[2];
; #pragma unroll
;       for (int n = 0; n < NB; ++n) {
;         float v[4];
; #pragma unroll
;         for (int j = 0; j < 4; ++j) { v[j] = acc[m][n][j] * rs; if (sig) v[j] = __builtin_amdgcn_rcpf(1.f + __expf(-v[j])); }
;         ob[n][0] = pk_bf16(v[0], v[1]); ob[n][1] = pk_bf16(v[2], v[3]);
;       }
;       *(i32x4*)(orow + wofs) = widen16(ob[0], ob[1]);
;     }
.LBB0_254:
	s_cmp_eq_u64 s[8:9], 0
	s_cbranch_scc1 .Lwin_fast_4
	v_lshl_add_u32 v35, v34, 2, s19
	ds_read2_b32 v[36:37], v35 offset1:16
	s_add_u32 s6, s56, s6
	s_addc_u32 s7, s57, s7
	s_add_i32 s13, s29, s24
	v_add_u32_e32 v32, s13, v32
	s_waitcnt lgkmcnt(0)
	v_mul_f32_e32 v36, s23, v36
	v_mul_f32_e32 v28, v28, v36
	v_mul_f32_e32 v38, 0xbfb8aa3b, v28
	v_exp_f32_e32 v38, v38
	v_mul_f32_e32 v29, v29, v36
	v_mul_f32_e32 v30, v30, v36
	v_mul_f32_e32 v31, v31, v36
	v_add_f32_e32 v38, 1.0, v38
	v_rcp_f32_e32 v38, v38
	v_mul_f32_e32 v24, v24, v36
	v_mul_f32_e32 v25, v25, v36
	v_mul_f32_e32 v26, v26, v36
	v_cndmask_b32_e64 v28, v28, v38, s[8:9]
	v_mul_f32_e32 v38, 0xbfb8aa3b, v29
	v_exp_f32_e32 v38, v38
	v_mul_f32_e32 v27, v27, v36
	v_ashrrev_i32_e32 v33, 31, v32
	v_lshl_add_u64 v[32:33], v[32:33], 1, s[6:7]
	v_add_f32_e32 v38, 1.0, v38
	v_rcp_f32_e32 v38, v38
	v_add_u32_e32 v34, s28, v34
	v_lshl_add_u64 v[32:33], v[194:195], 1, v[32:33]
	v_cndmask_b32_e64 v29, v29, v38, s[8:9]
	v_mul_f32_e32 v38, 0xbfb8aa3b, v30
	v_exp_f32_e32 v38, v38
	v_cvt_pk_bf16_f32 v28, v28, v29
	v_add_f32_e32 v38, 1.0, v38
	v_rcp_f32_e32 v38, v38
	s_nop 0
	v_cndmask_b32_e64 v30, v30, v38, s[8:9]
	v_mul_f32_e32 v38, 0xbfb8aa3b, v31
	v_exp_f32_e32 v38, v38
	s_nop 0
	v_add_f32_e32 v38, 1.0, v38
	v_rcp_f32_e32 v38, v38
	s_nop 0
	v_cndmask_b32_e64 v31, v31, v38, s[8:9]
	v_cvt_pk_bf16_f32 v29, v30, v31
	v_mul_f32_e32 v30, 0xbfb8aa3b, v24
	v_exp_f32_e32 v30, v30
	s_nop 0
	v_add_f32_e32 v30, 1.0, v30
	v_rcp_f32_e32 v30, v30
	s_nop 0
	v_cndmask_b32_e64 v24, v24, v30, s[8:9]
	v_mul_f32_e32 v30, 0xbfb8aa3b, v25
	v_exp_f32_e32 v30, v30
	s_nop 0
	v_add_f32_e32 v30, 1.0, v30
	v_rcp_f32_e32 v30, v30
	s_nop 0
	v_cndmask_b32_e64 v25, v25, v30, s[8:9]
	v_mul_f32_e32 v30, 0xbfb8aa3b, v26
	v_exp_f32_e32 v30, v30
	s_nop 0
	v_add_f32_e32 v30, 1.0, v30
	v_rcp_f32_e32 v30, v30
	s_nop 0
	v_cndmask_b32_e64 v26, v26, v30, s[8:9]
	v_mul_f32_e32 v30, 0xbfb8aa3b, v27
	v_exp_f32_e32 v30, v30
	s_nop 0
	v_add_f32_e32 v30, 1.0, v30
	v_rcp_f32_e32 v30, v30
	s_nop 0
	v_cndmask_b32_e64 v27, v27, v30, s[8:9]
	v_cvt_pk_bf16_f32 v30, v24, v25
	v_cvt_pk_bf16_f32 v31, v26, v27
	v_mad_i64_i32 v[24:25], s[6:7], s12, v34, 0
	v_permlane16_swap_b32_e32 v28, v30
	v_permlane16_swap_b32_e32 v29, v31
	v_lshl_add_u64 v[24:25], v[24:25], 1, v[32:33]
	global_store_dwordx4 v[24:25], v[28:31], off
	v_mul_f32_e32 v24, s23, v37
	v_mul_f32_e32 v20, v20, v24
	v_mul_f32_e32 v26, 0xbfb8aa3b, v20
	v_exp_f32_e32 v26, v26
	v_mul_f32_e32 v21, v21, v24
	v_mul_f32_e32 v22, v22, v24
	v_mul_f32_e32 v23, v23, v24
	v_add_f32_e32 v26, 1.0, v26
	v_rcp_f32_e32 v26, v26
	v_mul_f32_e32 v16, v16, v24
	v_mul_f32_e32 v17, v17, v24
	v_mul_f32_e32 v18, v18, v24
	v_cndmask_b32_e64 v20, v20, v26, s[8:9]
	v_mul_f32_e32 v26, 0xbfb8aa3b, v21
	v_exp_f32_e32 v26, v26
	v_mul_f32_e32 v19, v19, v24
	v_add_u32_e32 v25, 16, v34
	v_add_f32_e32 v26, 1.0, v26
	v_rcp_f32_e32 v26, v26
	s_nop 0
	v_cndmask_b32_e64 v21, v21, v26, s[8:9]
	v_mul_f32_e32 v26, 0xbfb8aa3b, v22
	v_exp_f32_e32 v26, v26
	v_cvt_pk_bf16_f32 v20, v20, v21
	v_add_f32_e32 v26, 1.0, v26
	v_rcp_f32_e32 v26, v26
	s_nop 0
	v_cndmask_b32_e64 v22, v22, v26, s[8:9]
	v_mul_f32_e32 v26, 0xbfb8aa3b, v23
	v_exp_f32_e32 v26, v26
	s_nop 0
	v_add_f32_e32 v26, 1.0, v26
	v_rcp_f32_e32 v26, v26
	s_nop 0
	v_cndmask_b32_e64 v23, v23, v26, s[8:9]
	v_cvt_pk_bf16_f32 v21, v22, v23
	v_mul_f32_e32 v22, 0xbfb8aa3b, v16
	v_exp_f32_e32 v22, v22
	s_nop 0
	v_add_f32_e32 v22, 1.0, v22
	v_rcp_f32_e32 v22, v22
	s_nop 0
	v_cndmask_b32_e64 v16, v16, v22, s[8:9]
	v_mul_f32_e32 v22, 0xbfb8aa3b, v17
	v_exp_f32_e32 v22, v22
	s_nop 0
	v_add_f32_e32 v22, 1.0, v22
	v_rcp_f32_e32 v22, v22
	s_nop 0
	v_cndmask_b32_e64 v17, v17, v22, s[8:9]
	v_mul_f32_e32 v22, 0xbfb8aa3b, v18
	v_exp_f32_e32 v22, v22
	s_nop 0
	v_add_f32_e32 v22, 1.0, v22
	v_rcp_f32_e32 v22, v22
	s_nop 0
	v_cndmask_b32_e64 v18, v18, v22, s[8:9]
	v_mul_f32_e32 v22, 0xbfb8aa3b, v19
	v_exp_f32_e32 v22, v22
	s_nop 0
	v_add_f32_e32 v22, 1.0, v22
	v_rcp_f32_e32 v22, v22
	s_nop 0
	v_cndmask_b32_e64 v19, v19, v22, s[8:9]
	v_cvt_pk_bf16_f32 v22, v16, v17
	v_cvt_pk_bf16_f32 v23, v18, v19
	v_mad_i64_i32 v[16:17], s[6:7], s12, v25, 0
	v_permlane16_swap_b32_e32 v20, v22
	v_permlane16_swap_b32_e32 v21, v23
	v_lshl_add_u64 v[16:17], v[16:17], 1, v[32:33]
	global_store_dwordx4 v[16:17], v[20:23], off
	ds_read2_b32 v[16:17], v35 offset0:32 offset1:48
	v_add_u32_e32 v18, 32, v34
	s_waitcnt lgkmcnt(0)
; template <int EPI, int MB, int NB> ...
;     ...
; #pragma unroll
;     for (int m = 0; m < MB; ++m) {
;       const int lr = lrow0 + m * 16;
;       const float rs = s_rstd[lr] * qs;
;       u16* orow = dst + (size_t)(brow + lr) * ld + (col0 - cb);
;       u32x2 ob[2];
; #pragma unroll
;       for (int n = 0; n < NB; ++n) {
;         float v[4];
; #pragma unroll
;         for (int j = 0; j < 4; ++j) { v[j] = acc[m][n][j] * rs; if (sig) v[j] = __builtin_amdgcn_rcpf(1.f + __expf(-v[j])); }
;         ob[n][0] = pk_bf16(v[0], v[1]); ob[n][1] = pk_bf16(v[2], v[3]);
;       }
;       *(i32x4*)(orow + wofs) = widen16(ob[0], ob[1]);
;     }
; template <int EPI, bool SWP> ...
;     ...
;   if (!prefetched) __syncthreads();
;   if (!prefetched && e.nss > 0 && tid < 256) {
;     float s = 0.f;
;     for (int i = 0; i < e.nss; ++i) s += e.ss[(size_t)(brow + tid) * e.nss + i];
;     s_rstd[tid] = rsqrtf(s * (1.f / DM) + 1e-6f);
	v_mul_f32_e32 v16, s23, v16
	v_mul_f32_e32 v12, v12, v16
	v_mul_f32_e32 v19, 0xbfb8aa3b, v12
	v_exp_f32_e32 v19, v19
	v_mul_f32_e32 v13, v13, v16
	v_mul_f32_e32 v14, v14, v16
	v_mul_f32_e32 v15, v15, v16
	v_add_f32_e32 v19, 1.0, v19
	v_rcp_f32_e32 v19, v19
	v_mul_f32_e32 v8, v8, v16
	v_mul_f32_e32 v9, v9, v16
	v_mul_f32_e32 v10, v10, v16
	v_cndmask_b32_e64 v12, v12, v19, s[8:9]
	v_mul_f32_e32 v19, 0xbfb8aa3b, v13
	v_exp_f32_e32 v19, v19
	v_mul_f32_e32 v11, v11, v16
	v_add_f32_e32 v19, 1.0, v19
	v_rcp_f32_e32 v19, v19
	s_nop 0
	v_cndmask_b32_e64 v13, v13, v19, s[8:9]
	v_mul_f32_e32 v19, 0xbfb8aa3b, v14
	v_exp_f32_e32 v19, v19
	v_cvt_pk_bf16_f32 v12, v12, v13
	v_add_f32_e32 v19, 1.0, v19
	v_rcp_f32_e32 v19, v19
	s_nop 0
	v_cndmask_b32_e64 v14, v14, v19, s[8:9]
	v_mul_f32_e32 v19, 0xbfb8aa3b, v15
	v_exp_f32_e32 v19, v19
	s_nop 0
	v_add_f32_e32 v19, 1.0, v19
	v_rcp_f32_e32 v19, v19
	s_nop 0
	v_cndmask_b32_e64 v15, v15, v19, s[8:9]
	v_cvt_pk_bf16_f32 v13, v14, v15
	v_mul_f32_e32 v14, 0xbfb8aa3b, v8
	v_exp_f32_e32 v14, v14
	s_nop 0
	v_add_f32_e32 v14, 1.0, v14
	v_rcp_f32_e32 v14, v14
	s_nop 0
	v_cndmask_b32_e64 v8, v8, v14, s[8:9]
	v_mul_f32_e32 v14, 0xbfb8aa3b, v9
	v_exp_f32_e32 v14, v14
	s_nop 0
	v_add_f32_e32 v14, 1.0, v14
	v_rcp_f32_e32 v14, v14
	s_nop 0
	v_cndmask_b32_e64 v9, v9, v14, s[8:9]
	v_mul_f32_e32 v14, 0xbfb8aa3b, v10
	v_exp_f32_e32 v14, v14
	s_nop 0
	v_add_f32_e32 v14, 1.0, v14
	v_rcp_f32_e32 v14, v14
	s_nop 0
	v_cndmask_b32_e64 v10, v10, v14, s[8:9]
	v_mul_f32_e32 v14, 0xbfb8aa3b, v11
	v_exp_f32_e32 v14, v14
	s_nop 0
	v_add_f32_e32 v14, 1.0, v14
	v_rcp_f32_e32 v14, v14
	s_nop 0
	v_cndmask_b32_e64 v11, v11, v14, s[8:9]
	v_cvt_pk_bf16_f32 v14, v8, v9
	v_cvt_pk_bf16_f32 v15, v10, v11
	v_mad_i64_i32 v[8:9], s[6:7], s12, v18, 0
	v_permlane16_swap_b32_e32 v12, v14
	v_permlane16_swap_b32_e32 v13, v15
	v_lshl_add_u64 v[8:9], v[8:9], 1, v[32:33]
	global_store_dwordx4 v[8:9], v[12:15], off
	v_mul_f32_e32 v8, s23, v17
	v_mul_f32_e32 v4, v4, v8
	v_mul_f32_e32 v10, 0xbfb8aa3b, v4
	v_exp_f32_e32 v10, v10
	v_mul_f32_e32 v5, v5, v8
	v_mul_f32_e32 v6, v6, v8
	v_mul_f32_e32 v7, v7, v8
	v_add_f32_e32 v10, 1.0, v10
	v_rcp_f32_e32 v10, v10
	v_mul_f32_e32 v0, v0, v8
	v_mul_f32_e32 v1, v1, v8
	v_mul_f32_e32 v2, v2, v8
	v_cndmask_b32_e64 v4, v4, v10, s[8:9]
	v_mul_f32_e32 v10, 0xbfb8aa3b, v5
	v_exp_f32_e32 v10, v10
	v_mul_f32_e32 v3, v3, v8
	v_add_u32_e32 v9, 48, v34
	v_add_f32_e32 v10, 1.0, v10
	v_rcp_f32_e32 v10, v10
	s_nop 0
	v_cndmask_b32_e64 v5, v5, v10, s[8:9]
	v_mul_f32_e32 v10, 0xbfb8aa3b, v6
	v_exp_f32_e32 v10, v10
	v_cvt_pk_bf16_f32 v4, v4, v5
	v_add_f32_e32 v10, 1.0, v10
	v_rcp_f32_e32 v10, v10
	s_nop 0
	v_cndmask_b32_e64 v6, v6, v10, s[8:9]
	v_mul_f32_e32 v10, 0xbfb8aa3b, v7
	v_exp_f32_e32 v10, v10
	s_nop 0
	v_add_f32_e32 v10, 1.0, v10
	v_rcp_f32_e32 v10, v10
	s_nop 0
	v_cndmask_b32_e64 v7, v7, v10, s[8:9]
	v_cvt_pk_bf16_f32 v5, v6, v7
	v_mul_f32_e32 v6, 0xbfb8aa3b, v0
	v_exp_f32_e32 v6, v6
	s_nop 0
	v_add_f32_e32 v6, 1.0, v6
	v_rcp_f32_e32 v6, v6
	s_nop 0
	v_cndmask_b32_e64 v0, v0, v6, s[8:9]
	v_mul_f32_e32 v6, 0xbfb8aa3b, v1
	v_exp_f32_e32 v6, v6
	s_nop 0
	v_add_f32_e32 v6, 1.0, v6
	v_rcp_f32_e32 v6, v6
	s_nop 0
	v_cndmask_b32_e64 v1, v1, v6, s[8:9]
	v_mul_f32_e32 v6, 0xbfb8aa3b, v2
	v_exp_f32_e32 v6, v6
	s_nop 0
	v_add_f32_e32 v6, 1.0, v6
	v_rcp_f32_e32 v6, v6
	s_nop 0
	v_cndmask_b32_e64 v2, v2, v6, s[8:9]
	v_mul_f32_e32 v6, 0xbfb8aa3b, v3
	v_exp_f32_e32 v6, v6
	s_nop 0
	v_add_f32_e32 v6, 1.0, v6
	v_rcp_f32_e32 v6, v6
	s_nop 0
	v_cndmask_b32_e64 v3, v3, v6, s[8:9]
	v_cvt_pk_bf16_f32 v6, v0, v1
	v_cvt_pk_bf16_f32 v7, v2, v3
	v_mad_i64_i32 v[0:1], s[6:7], s12, v9, 0
	v_permlane16_swap_b32_e32 v4, v6
	v_permlane16_swap_b32_e32 v5, v7
	v_lshl_add_u64 v[0:1], v[0:1], 1, v[32:33]
	s_mov_b64 s[6:7], 0
	global_store_dwordx4 v[0:1], v[4:7], off
.Lwin_join_4:
.LBB0_255:
	s_and_b64 vcc, exec, s[6:7]
	s_cbranch_vccz .LBB0_180
	s_and_b64 vcc, exec, s[10:11]
	s_mov_b64 s[6:7], -1
	s_cbranch_vccnz .LBB0_262
	s_waitcnt vmcnt(0)
	s_barrier
	s_mov_b64 s[6:7], exec
	v_readlane_b32 s8, v254, 60
	v_readlane_b32 s9, v254, 61
	s_and_b64 s[8:9], s[6:7], s[8:9]
	s_mov_b64 exec, s[8:9]
	s_cbranch_execz .LBB0_259
	v_add_u32_e32 v0, s28, v202
	v_ashrrev_i32_e32 v1, 31, v0
	v_readlane_b32 s8, v254, 50
	v_lshlrev_b64 v[0:1], 5, v[0:1]
	v_readlane_b32 s9, v254, 51
	s_nop 1
	v_lshl_add_u64 v[4:5], s[8:9], 0, v[0:1]
	global_load_dwordx4 v[0:3], v[4:5], off
	s_nop 0
	global_load_dwordx4 v[4:7], v[4:5], off offset:16
	s_mov_b32 s8, 0x800000
	s_waitcnt vmcnt(1)
	v_add_f32_e32 v0, 0, v0
	v_add_f32_e32 v0, v0, v1
	v_add_f32_e32 v0, v0, v2
	v_add_f32_e32 v0, v0, v3
	s_waitcnt vmcnt(0)
	v_add_f32_e32 v0, v0, v4
	v_add_f32_e32 v0, v0, v5
	v_add_f32_e32 v0, v0, v6
	v_add_f32_e32 v0, v0, v7
	v_fmamk_f32 v0, v0, 0x3a000000, v223
	v_mul_f32_e32 v1, 0x4b800000, v0
	v_cmp_gt_f32_e32 vcc, s8, v0
	s_nop 1
	v_cndmask_b32_e32 v0, v0, v1, vcc
	v_rsq_f32_e32 v0, v0
	s_nop 0
	v_mul_f32_e32 v1, 0x45800000, v0
	v_cndmask_b32_e32 v0, v0, v1, vcc
	v_lshl_add_u32 v1, v202, 2, s19
	ds_write_b32 v1, v0
